# v35: v33 + SSD chunk loop: the next chunk's register-staged prefetch loads (address math + 4 global loads) moved from the head of the chunk step behind the first four LDS reads
# baseline (speedup 1.0000x reference)
; #define LAS __attribute__((address_space(3)))
; __device__ __forceinline__ unsigned pkbf(float lo, float hi) { f32x2v v = {lo, hi}; bf16x2v b = __builtin_convertvector(v, bf16x2v); return __builtin_bit_cast(unsigned, b); }
; #define MFMA16(a, b, c) __builtin_amdgcn_mfma_f32_16x16x32_bf16((a), (b), (c), 0, 0, 0)
; #define SSD_GLOAD(c_) do { const size_t gr_ = (size_t)rb + (size_t)(c_) * 64 + 16 * ib + l15; _Pragma("unroll") for (int pt = 0; pt < 2; ++pt) { const int p0 = 16 * (2 * (wid & 1) + pt) + 4 * quad; \
;         ngx[pt] = *(const u32x2*)(XBC + gr_ * 4096 + h * 64 + p0); ngz[pt] = *(const u32x2*)(PROJ + gr_ * NIN + PC_Z + h * 64 + p0); } } while (0)
; DI void ssd_unit(LAS unsigned char* lds, const bf16* XBC, const float* DT, const bf16* PROJ, bf16* YG, int rb, int NC, int h, float A, float Dsk, const float* h0, float* hout, int tid) {
;     ...
;     for (int c = 0; c < NC; ++c) {
;         const int row0 = rb + c * 64, ts = c & 1;
;         const LAS unsigned char* T = lds + ts * TSET;
;         const LAS unsigned char* Hc = lds + HS + ts * HSET; LAS unsigned char* Hn = lds + HS + (ts ^ 1) * HSET;
;         const int i = 16 * ib + l15; const float ac_i = __shfl(ac, i);
;         u32x2 gx[2], gz[2];
; #pragma unroll
;         for (int pt = 0; pt < 2; ++pt) { gx[pt] = ngx[pt]; gz[pt] = ngz[pt]; }
;         if (c + 1 < NC) SSD_GLOAD(c + 1);
;         bf16x8 cf[4];
; #pragma unroll
;         for (int s = 0; s < 4; ++s) cf[s] = row_frag(T + CS, RSC, 16 * ib + l15, 32 * s, lane);
; #pragma unroll
;         for (int jt = 0; jt < 2; ++jt) {
;             const int jb = 2 * (wid & 1) + jt; u32x2 w = {0u, 0u};
;             if (jb <= ib) {
;                 f32x4 acc = {0.f, 0.f, 0.f, 0.f};
; #pragma unroll
;                 for (int s = 0; s < 4; ++s) acc = MFMA16(row_frag(T + BS, RSC, 16 * jb + l15, 32 * s, lane), cf[s], acc);
;                 float v[4];
; #pragma unroll
;                 for (int r = 0; r < 4; ++r) { const int j = 16 * jb + 4 * quad + r; const float ac_j = __shfl(ac, j); v[r] = (j <= i) ? acc[r] * __expf(ac_i - ac_j) : 0.f; }
;                 w.x = pkbf(v[0], v[1]); w.y = pkbf(v[2], v[3]);
;             }
;             *(LAS u32x2*)(lds + LS + i * RSX + (16 * jb + 4 * quad) * 2) = w;
.LBB0_1146:
	s_and_b32 s64, s63, 1
	s_mul_i32 s26, s64, 0xd000
	s_add_i32 s62, s26, 0
	v_add_u32_e32 v99, s62, v149
	v_add_u32_e32 v1, v99, v148
	ds_read_b128 v[60:63], v1
	ds_read_b128 v[56:59], v1 offset:64
	ds_read_b128 v[52:55], v1 offset:128
	ds_read_b128 v[48:51], v1 offset:192
	s_cmp_ge_u32 s10, s9
	s_cbranch_scc1 .Lssd_nopref
	v_lshl_add_u64 v[64:65], s[78:79], 0, v[104:105]
	v_add_co_u32_e32 v64, vcc, 0x5b5e0000, v64
	v_lshl_add_u64 v[66:67], s[78:79], 0, v[116:117]
	s_nop 0
	v_addc_co_u32_e32 v65, vcc, 0, v65, vcc
	v_add_co_u32_e32 v66, vcc, 0x4b698000, v66
	s_nop 1
	v_addc_co_u32_e32 v67, vcc, 0, v67, vcc
	global_load_dwordx2 v[118:119], v[64:65], off
	global_load_dwordx2 v[122:123], v[66:67], off offset:3072
	global_load_dwordx2 v[124:125], v[66:67], off offset:3104
	global_load_dwordx2 v[120:121], v[64:65], off offset:32
.Lssd_nopref:
	v_mov_b32_e32 v64, 0
	v_mov_b32_e32 v66, 0
	v_mov_b32_e32 v67, 0
	s_and_saveexec_b64 s[26:27], s[38:39]
	s_cbranch_execz .LBB0_1148
	v_add_u32_e32 v1, v99, v155
	ds_read_b128 v[134:137], v1 offset:17408
	ds_read_b128 v[172:175], v1 offset:17472
	ds_bpermute_b32 v65, v157, v171
	ds_bpermute_b32 v66, v158, v171
	ds_bpermute_b32 v67, v159, v171
	s_waitcnt lgkmcnt(4)
	v_mfma_f32_16x16x32_bf16 v[134:137], v[134:137], v[60:63], 0
	s_waitcnt lgkmcnt(2)
	v_sub_f32_e32 v65, v97, v65
	v_mul_f32_e32 v65, 0x3fb8aa3b, v65
	s_waitcnt lgkmcnt(1)
	v_sub_f32_e32 v66, v97, v66
	v_mfma_f32_16x16x32_bf16 v[134:137], v[172:175], v[56:59], v[134:137]
	ds_read_b128 v[172:175], v1 offset:17536
	s_waitcnt lgkmcnt(1)
	v_sub_f32_e32 v67, v97, v67
	v_exp_f32_e32 v65, v65
	v_mul_f32_e32 v66, 0x3fb8aa3b, v66
	v_mul_f32_e32 v67, 0x3fb8aa3b, v67
	v_exp_f32_e32 v66, v66
	v_exp_f32_e32 v67, v67
	s_waitcnt lgkmcnt(0)
	v_mfma_f32_16x16x32_bf16 v[134:137], v[172:175], v[52:55], v[134:137]
	ds_read_b128 v[172:175], v1 offset:17600
	ds_bpermute_b32 v1, v156, v171
	s_waitcnt lgkmcnt(0)
	v_sub_f32_e32 v1, v97, v1
	v_mul_f32_e32 v1, 0x3fb8aa3b, v1
	v_mfma_f32_16x16x32_bf16 v[134:137], v[172:175], v[48:51], v[134:137]
	v_exp_f32_e32 v1, v1
	s_nop 6
	v_mul_f32_e32 v1, v134, v1
	v_mul_f32_e32 v65, v135, v65
	v_cndmask_b32_e64 v1, v1, 0, s[40:41]
	v_cndmask_b32_e64 v65, 0, v65, s[42:43]
	v_pk_mul_f32 v[134:135], v[136:137], v[66:67]
	v_cvt_pk_bf16_f32 v66, v1, v65
	v_cvt_pk_bf16_f32 v1, v134, v135
	v_cndmask_b32_e64 v65, v1, 0, s[46:47]
	v_lshrrev_b32_e32 v1, 16, v1
	v_cndmask_b32_e64 v1, v1, 0, s[44:45]
	v_perm_b32 v67, v1, v65, s87
